# loop-edge edit: K-loop tail scalar pointer/counter updates moved ahead of the closing barrier (into the MFMA shadow) in all three GEMM loops (on top of v54)
# speedup vs baseline: 1.0036x; 1.0036x over previous
; #define PG8_STAGE(bufoff, gbase, voff) do { _Pragma("unroll") for (int _i = 0; _i < 2; ++_i) \
;         __builtin_amdgcn_global_load_lds((const unsigned*)((const char*)(gbase) + (voff)[_i]), (LAS unsigned*)(lds + (bufoff) + ldsw + _i * 8192), 16, 0, 0); } while (0)
; #define PG8_LDA(dst, b, h) do { _Pragma("unroll") for (int m = 0; m < 4; ++m) _Pragma("unroll") for (int k = 0; k < 2; ++k) dst[m][k] = *(const LAS bf16x8*)(lds + PG8_SA(b, h) + aoff + m * 2048 + k * 1024); } while (0)
; #define PG8_LDB(dst, b, h) do { _Pragma("unroll") for (int n = 0; n < 2; ++n) _Pragma("unroll") for (int k = 0; k < 2; ++k) dst[n][k] = *(const LAS bf16x8*)(lds + PG8_SB(b, h) + boff + n * 2048 + k * 1024); } while (0)
; #define PG8_MMA(ai, bj, At, Bt) do { __builtin_amdgcn_s_setprio(1); _Pragma("unroll") for (int m = 0; m < 4; ++m) _Pragma("unroll") for (int n = 0; n < 2; ++n) _Pragma("unroll") for (int k = 0; k < 2; ++k) \
;         acc[ai][bj][m][n] = __builtin_amdgcn_mfma_f32_16x16x32_bf16(Bt[n][k], At[m][k], acc[ai][bj][m][n], 0, 0, 0); __builtin_amdgcn_s_setprio(0); } while (0)
; #define PG8_WAIT_V(n) asm volatile("s_waitcnt vmcnt(" #n ")" ::: "memory")
; #define PG8_WAIT_L(n) asm volatile("s_waitcnt lgkmcnt(" #n ")" ::: "memory")
; #define PG8_BAR __builtin_amdgcn_s_barrier()
; #define PG8_SCHED __builtin_amdgcn_sched_barrier(0)
; template <class Epi, class Sched>
; __device__ __forceinline__ void gemm_phase(LAS unsigned char* lds, const int lda, const int ldb, const Sched& S, const Epi& E) {
;     ...
;         for (int t = 0; t < nt; t += 2) {
;             const bool last = (t == nt - 2);
;             const char* a1 = cA + (size_t)(t + 1) * kstep;
;             const char* a2 = last ? nA : cA + (size_t)(t + 2) * kstep; const char* b2 = last ? nB : cB + (size_t)(t + 2) * kstep;
;             const char* a3 = a2 + kstep; const char* b3 = b2 + kstep;
;             PG8_LDB(B0, 0, 0); PG8_LDB(B1, 0, 1); PG8_SCHED; PG8_LDA(At, 0, 0); PG8_STAGE(PG8_SA(1, 1), a1 + hstepA, voffA);
;             PG8_WAIT_V(8); PG8_WAIT_L(0); PG8_BAR; PG8_MMA(0, 0, At, B0); PG8_MMA(0, 1, At, B1); PG8_BAR; PG8_SCHED;
;             PG8_LDA(At, 0, 1); PG8_STAGE(PG8_SB(0, 0), b2, voffB); PG8_STAGE(PG8_SB(0, 1), b2 + hstepB, voffB); PG8_STAGE(PG8_SA(0, 0), a2, voffA);
.LBB0_206:
	s_add_u32 s36, s22, 0x100
	s_addc_u32 s37, s23, 0
	s_add_i32 s58, 0, 0x10000
	s_cmp_eq_u32 s38, 12
	s_cselect_b32 s47, s17, s37
	s_cselect_b32 s46, s16, s36
	s_cselect_b32 s45, s21, s25
	s_cselect_b32 s44, s20, s24
	s_add_i32 s59, 0, 0x14000
	v_add_u32_e32 v154, s58, v159
	v_add_u32_e32 v163, s59, v159
	ds_read_b128 v[142:145], v154
	ds_read_b128 v[146:149], v154 offset:1024
	ds_read_b128 v[150:153], v154 offset:2048
	ds_read_b128 v[154:157], v154 offset:3072
	ds_read_b128 v[164:167], v163
	ds_read_b128 v[168:171], v163 offset:1024
	ds_read_b128 v[172:175], v163 offset:2048
	ds_read_b128 v[176:179], v163 offset:3072
	v_lshl_add_u64 v[192:193], s[22:23], 0, v[138:139]
	s_add_i32 m0, s29, 0xc000
	ds_read_b128 v[180:183], v162
	ds_read_b128 v[184:187], v162 offset:1024
	ds_read_b128 v[188:191], v162 offset:2048
	ds_read_b128 v[206:209], v162 offset:3072
	ds_read_b128 v[210:213], v162 offset:4096
	ds_read_b128 v[214:217], v162 offset:5120
	ds_read_b128 v[218:221], v162 offset:6144
	ds_read_b128 v[222:225], v162 offset:7168
	global_load_lds_dwordx4 v[192:193], off
	v_lshl_add_u64 v[192:193], s[22:23], 0, v[140:141]
	s_add_i32 m0, s29, 0xe000
	s_nop 0
	global_load_lds_dwordx4 v[192:193], off
	s_waitcnt vmcnt(8)
	s_waitcnt lgkmcnt(0)
	s_barrier
	s_setprio 1
	s_waitcnt lgkmcnt(0)
	v_mfma_f32_16x16x32_bf16 v[126:129], v[142:145], v[180:183], v[126:129]
	v_mfma_f32_16x16x32_bf16 v[122:125], v[150:153], v[180:183], v[122:125]
	v_mfma_f32_16x16x32_bf16 v[118:121], v[142:145], v[188:191], v[118:121]
	v_mfma_f32_16x16x32_bf16 v[110:113], v[150:153], v[188:191], v[110:113]
	v_mfma_f32_16x16x32_bf16 v[102:105], v[142:145], v[210:213], v[102:105]
	v_mfma_f32_16x16x32_bf16 v[94:97], v[150:153], v[210:213], v[94:97]
	v_mfma_f32_16x16x32_bf16 v[86:89], v[142:145], v[218:221], v[86:89]
	v_mfma_f32_16x16x32_bf16 v[78:81], v[150:153], v[218:221], v[78:81]
	v_mfma_f32_16x16x32_bf16 v[126:129], v[146:149], v[184:187], v[126:129]
	v_mfma_f32_16x16x32_bf16 v[122:125], v[154:157], v[184:187], v[122:125]
	v_mfma_f32_16x16x32_bf16 v[118:121], v[146:149], v[206:209], v[118:121]
	v_mfma_f32_16x16x32_bf16 v[110:113], v[154:157], v[206:209], v[110:113]
	v_mfma_f32_16x16x32_bf16 v[102:105], v[146:149], v[214:217], v[102:105]
	v_mfma_f32_16x16x32_bf16 v[94:97], v[154:157], v[214:217], v[94:97]
	v_mfma_f32_16x16x32_bf16 v[86:89], v[146:149], v[222:225], v[86:89]
	v_mfma_f32_16x16x32_bf16 v[78:81], v[154:157], v[222:225], v[78:81]
	s_setprio 0
	s_setprio 1
	v_mfma_f32_16x16x32_bf16 v[114:117], v[164:167], v[180:183], v[114:117]
	v_mfma_f32_16x16x32_bf16 v[106:109], v[172:175], v[180:183], v[106:109]
	v_mfma_f32_16x16x32_bf16 v[98:101], v[164:167], v[188:191], v[98:101]
	v_mfma_f32_16x16x32_bf16 v[90:93], v[172:175], v[188:191], v[90:93]
	v_mfma_f32_16x16x32_bf16 v[82:85], v[164:167], v[210:213], v[82:85]
	v_mfma_f32_16x16x32_bf16 v[74:77], v[172:175], v[210:213], v[74:77]
	v_mfma_f32_16x16x32_bf16 v[70:73], v[164:167], v[218:221], v[70:73]
	v_mfma_f32_16x16x32_bf16 v[66:69], v[172:175], v[218:221], v[66:69]
	v_mfma_f32_16x16x32_bf16 v[114:117], v[168:171], v[184:187], v[114:117]
	v_mfma_f32_16x16x32_bf16 v[106:109], v[176:179], v[184:187], v[106:109]
	v_mfma_f32_16x16x32_bf16 v[98:101], v[168:171], v[206:209], v[98:101]
	v_mfma_f32_16x16x32_bf16 v[90:93], v[176:179], v[206:209], v[90:93]
	v_mfma_f32_16x16x32_bf16 v[82:85], v[168:171], v[214:217], v[82:85]
	v_mfma_f32_16x16x32_bf16 v[74:77], v[176:179], v[214:217], v[74:77]
	v_mfma_f32_16x16x32_bf16 v[70:73], v[168:171], v[222:225], v[70:73]
	v_mfma_f32_16x16x32_bf16 v[66:69], v[176:179], v[222:225], v[66:69]
	s_setprio 0
	s_barrier
	s_add_i32 s22, s58, s26
	v_lshl_add_u64 v[192:193], s[44:45], 0, v[134:135]
	s_mov_b32 m0, s22
	ds_read_b128 v[180:183], v162 offset:16384
	ds_read_b128 v[184:187], v162 offset:17408
	ds_read_b128 v[188:191], v162 offset:18432
	ds_read_b128 v[206:209], v162 offset:19456
	ds_read_b128 v[210:213], v162 offset:20480
	ds_read_b128 v[214:217], v162 offset:21504
	ds_read_b128 v[218:221], v162 offset:22528
	ds_read_b128 v[222:225], v162 offset:23552
	global_load_lds_dwordx4 v[192:193], off
	s_add_i32 m0, s22, 0x2000
	s_add_u32 s22, s44, 0x40000
	v_lshl_add_u64 v[240:241], s[44:45], 0, v[130:131]
	s_addc_u32 s23, s45, 0
	s_add_i32 s58, s59, s26
	global_load_lds_dwordx4 v[240:241], off
	v_lshl_add_u64 v[242:243], s[22:23], 0, v[134:135]
	s_mov_b32 m0, s58
	v_lshl_add_u64 v[244:245], s[46:47], 0, v[132:133]
	global_load_lds_dwordx4 v[242:243], off
	v_lshl_add_u64 v[242:243], s[22:23], 0, v[130:131]
	s_add_i32 m0, s58, 0x2000
	s_nop 0
	global_load_lds_dwordx4 v[242:243], off
	v_lshl_add_u64 v[242:243], s[46:47], 0, v[136:137]
	s_mov_b32 m0, s29
	s_nop 0
	global_load_lds_dwordx4 v[242:243], off
	s_mov_b32 m0, s33
	s_nop 0
	global_load_lds_dwordx4 v[244:245], off
	s_waitcnt vmcnt(8)
	s_waitcnt lgkmcnt(0)
	s_barrier
; #define PG8_STAGE(bufoff, gbase, voff) do { _Pragma("unroll") for (int _i = 0; _i < 2; ++_i) \
;         __builtin_amdgcn_global_load_lds((const unsigned*)((const char*)(gbase) + (voff)[_i]), (LAS unsigned*)(lds + (bufoff) + ldsw + _i * 8192), 16, 0, 0); } while (0)
; #define PG8_LDA(dst, b, h) do { _Pragma("unroll") for (int m = 0; m < 4; ++m) _Pragma("unroll") for (int k = 0; k < 2; ++k) dst[m][k] = *(const LAS bf16x8*)(lds + PG8_SA(b, h) + aoff + m * 2048 + k * 1024); } while (0)
; #define PG8_LDB(dst, b, h) do { _Pragma("unroll") for (int n = 0; n < 2; ++n) _Pragma("unroll") for (int k = 0; k < 2; ++k) dst[n][k] = *(const LAS bf16x8*)(lds + PG8_SB(b, h) + boff + n * 2048 + k * 1024); } while (0)
; #define PG8_MMA(ai, bj, At, Bt) do { __builtin_amdgcn_s_setprio(1); _Pragma("unroll") for (int m = 0; m < 4; ++m) _Pragma("unroll") for (int n = 0; n < 2; ++n) _Pragma("unroll") for (int k = 0; k < 2; ++k) \
;         acc[ai][bj][m][n] = __builtin_amdgcn_mfma_f32_16x16x32_bf16(Bt[n][k], At[m][k], acc[ai][bj][m][n], 0, 0, 0); __builtin_amdgcn_s_setprio(0); } while (0)
; #define PG8_WAIT_V(n) asm volatile("s_waitcnt vmcnt(" #n ")" ::: "memory")
; #define PG8_WAIT_L(n) asm volatile("s_waitcnt lgkmcnt(" #n ")" ::: "memory")
; #define PG8_BAR __builtin_amdgcn_s_barrier()
; #define PG8_SCHED __builtin_amdgcn_sched_barrier(0)
; template <class Epi, class Sched>
; __device__ __forceinline__ void gemm_phase(LAS unsigned char* lds, const int lda, const int ldb, const Sched& S, const Epi& E) {
;     ...
;             PG8_WAIT_V(8); PG8_WAIT_L(0); PG8_BAR; PG8_MMA(1, 0, At, B0); PG8_MMA(1, 1, At, B1); PG8_BAR; PG8_SCHED;
;             PG8_LDB(B0, 1, 0); PG8_LDB(B1, 1, 1); PG8_SCHED; PG8_LDA(At, 1, 0); PG8_STAGE(PG8_SA(0, 1), a2 + hstepA, voffA);
;             PG8_WAIT_V(8); PG8_WAIT_L(0); PG8_BAR; PG8_MMA(0, 0, At, B0); PG8_MMA(0, 1, At, B1); PG8_BAR; PG8_SCHED;
	s_setprio 1
	s_waitcnt lgkmcnt(0)
	v_mfma_f32_16x16x32_bf16 v[62:65], v[142:145], v[180:183], v[62:65]
	v_mfma_f32_16x16x32_bf16 v[58:61], v[150:153], v[180:183], v[58:61]
	v_mfma_f32_16x16x32_bf16 v[54:57], v[142:145], v[188:191], v[54:57]
	v_mfma_f32_16x16x32_bf16 v[46:49], v[150:153], v[188:191], v[46:49]
	v_mfma_f32_16x16x32_bf16 v[38:41], v[142:145], v[210:213], v[38:41]
	v_mfma_f32_16x16x32_bf16 v[30:33], v[150:153], v[210:213], v[30:33]
	v_mfma_f32_16x16x32_bf16 v[22:25], v[142:145], v[218:221], v[22:25]
	v_mfma_f32_16x16x32_bf16 v[14:17], v[150:153], v[218:221], v[14:17]
	v_mfma_f32_16x16x32_bf16 v[62:65], v[146:149], v[184:187], v[62:65]
	v_mfma_f32_16x16x32_bf16 v[58:61], v[154:157], v[184:187], v[58:61]
	v_mfma_f32_16x16x32_bf16 v[54:57], v[146:149], v[206:209], v[54:57]
	v_mfma_f32_16x16x32_bf16 v[46:49], v[154:157], v[206:209], v[46:49]
	v_mfma_f32_16x16x32_bf16 v[38:41], v[146:149], v[214:217], v[38:41]
	v_mfma_f32_16x16x32_bf16 v[30:33], v[154:157], v[214:217], v[30:33]
	v_mfma_f32_16x16x32_bf16 v[22:25], v[146:149], v[222:225], v[22:25]
	v_mfma_f32_16x16x32_bf16 v[14:17], v[154:157], v[222:225], v[14:17]
	s_setprio 0
	s_setprio 1
	v_mfma_f32_16x16x32_bf16 v[50:53], v[164:167], v[180:183], v[50:53]
	v_mfma_f32_16x16x32_bf16 v[42:45], v[172:175], v[180:183], v[42:45]
	v_mfma_f32_16x16x32_bf16 v[34:37], v[164:167], v[188:191], v[34:37]
	v_mfma_f32_16x16x32_bf16 v[26:29], v[172:175], v[188:191], v[26:29]
	v_mfma_f32_16x16x32_bf16 v[18:21], v[164:167], v[210:213], v[18:21]
	v_mfma_f32_16x16x32_bf16 v[10:13], v[172:175], v[210:213], v[10:13]
	v_mfma_f32_16x16x32_bf16 v[6:9], v[164:167], v[218:221], v[6:9]
	v_mfma_f32_16x16x32_bf16 v[2:5], v[172:175], v[218:221], v[2:5]
	v_mfma_f32_16x16x32_bf16 v[50:53], v[168:171], v[184:187], v[50:53]
	v_mfma_f32_16x16x32_bf16 v[42:45], v[176:179], v[184:187], v[42:45]
	v_mfma_f32_16x16x32_bf16 v[34:37], v[168:171], v[206:209], v[34:37]
	v_mfma_f32_16x16x32_bf16 v[26:29], v[176:179], v[206:209], v[26:29]
	v_mfma_f32_16x16x32_bf16 v[18:21], v[168:171], v[214:217], v[18:21]
	v_mfma_f32_16x16x32_bf16 v[10:13], v[176:179], v[214:217], v[10:13]
	v_mfma_f32_16x16x32_bf16 v[6:9], v[168:171], v[222:225], v[6:9]
	v_mfma_f32_16x16x32_bf16 v[2:5], v[176:179], v[222:225], v[2:5]
	s_setprio 0
	s_barrier
	s_add_i32 s58, 0, 0x18000
	s_add_i32 s59, 0, 0x1c000
	v_add_u32_e32 v154, s58, v159
	v_add_u32_e32 v163, s59, v159
	ds_read_b128 v[142:145], v154
	ds_read_b128 v[146:149], v154 offset:1024
	ds_read_b128 v[150:153], v154 offset:2048
	ds_read_b128 v[154:157], v154 offset:3072
	ds_read_b128 v[164:167], v163
	ds_read_b128 v[168:171], v163 offset:1024
	ds_read_b128 v[172:175], v163 offset:2048
	ds_read_b128 v[176:179], v163 offset:3072
	s_add_u32 s22, s46, 0x190000
	s_addc_u32 s23, s47, 0
	s_mov_b32 m0, s48
	v_lshl_add_u64 v[246:247], s[22:23], 0, v[136:137]
	ds_read_b128 v[180:183], v162 offset:32768
	ds_read_b128 v[184:187], v162 offset:33792
	ds_read_b128 v[188:191], v162 offset:34816
	ds_read_b128 v[206:209], v162 offset:35840
	ds_read_b128 v[210:213], v162 offset:36864
	ds_read_b128 v[214:217], v162 offset:37888
	ds_read_b128 v[218:221], v162 offset:38912
	ds_read_b128 v[222:225], v162 offset:39936
	global_load_lds_dwordx4 v[246:247], off
	v_lshl_add_u64 v[246:247], s[22:23], 0, v[132:133]
	s_mov_b32 m0, s49
	s_nop 0
	global_load_lds_dwordx4 v[246:247], off
	s_waitcnt vmcnt(8)
	s_waitcnt lgkmcnt(0)
	s_barrier
	s_setprio 1
	s_waitcnt lgkmcnt(0)
	v_mfma_f32_16x16x32_bf16 v[126:129], v[142:145], v[180:183], v[126:129]
	v_mfma_f32_16x16x32_bf16 v[122:125], v[150:153], v[180:183], v[122:125]
	v_mfma_f32_16x16x32_bf16 v[118:121], v[142:145], v[188:191], v[118:121]
	v_mfma_f32_16x16x32_bf16 v[110:113], v[150:153], v[188:191], v[110:113]
	v_mfma_f32_16x16x32_bf16 v[102:105], v[142:145], v[210:213], v[102:105]
	v_mfma_f32_16x16x32_bf16 v[94:97], v[150:153], v[210:213], v[94:97]
	v_mfma_f32_16x16x32_bf16 v[86:89], v[142:145], v[218:221], v[86:89]
	v_mfma_f32_16x16x32_bf16 v[78:81], v[150:153], v[218:221], v[78:81]
	v_mfma_f32_16x16x32_bf16 v[126:129], v[146:149], v[184:187], v[126:129]
	v_mfma_f32_16x16x32_bf16 v[122:125], v[154:157], v[184:187], v[122:125]
	v_mfma_f32_16x16x32_bf16 v[118:121], v[146:149], v[206:209], v[118:121]
	v_mfma_f32_16x16x32_bf16 v[110:113], v[154:157], v[206:209], v[110:113]
	v_mfma_f32_16x16x32_bf16 v[102:105], v[146:149], v[214:217], v[102:105]
	v_mfma_f32_16x16x32_bf16 v[94:97], v[154:157], v[214:217], v[94:97]
	v_mfma_f32_16x16x32_bf16 v[86:89], v[146:149], v[222:225], v[86:89]
	v_mfma_f32_16x16x32_bf16 v[78:81], v[154:157], v[222:225], v[78:81]
	s_setprio 0
	s_setprio 1
	v_mfma_f32_16x16x32_bf16 v[114:117], v[164:167], v[180:183], v[114:117]
	v_mfma_f32_16x16x32_bf16 v[106:109], v[172:175], v[180:183], v[106:109]
	v_mfma_f32_16x16x32_bf16 v[98:101], v[164:167], v[188:191], v[98:101]
	v_mfma_f32_16x16x32_bf16 v[90:93], v[172:175], v[188:191], v[90:93]
	v_mfma_f32_16x16x32_bf16 v[82:85], v[164:167], v[210:213], v[82:85]
	v_mfma_f32_16x16x32_bf16 v[74:77], v[172:175], v[210:213], v[74:77]
	v_mfma_f32_16x16x32_bf16 v[70:73], v[164:167], v[218:221], v[70:73]
	v_mfma_f32_16x16x32_bf16 v[66:69], v[172:175], v[218:221], v[66:69]
	v_mfma_f32_16x16x32_bf16 v[114:117], v[168:171], v[184:187], v[114:117]
	v_mfma_f32_16x16x32_bf16 v[106:109], v[176:179], v[184:187], v[106:109]
	v_mfma_f32_16x16x32_bf16 v[98:101], v[168:171], v[206:209], v[98:101]
	v_mfma_f32_16x16x32_bf16 v[90:93], v[176:179], v[206:209], v[90:93]
	v_mfma_f32_16x16x32_bf16 v[82:85], v[168:171], v[214:217], v[82:85]
	v_mfma_f32_16x16x32_bf16 v[74:77], v[176:179], v[214:217], v[74:77]
	v_mfma_f32_16x16x32_bf16 v[70:73], v[168:171], v[222:225], v[70:73]
	v_mfma_f32_16x16x32_bf16 v[66:69], v[176:179], v[222:225], v[66:69]
	s_setprio 0
	s_barrier
; #define PG8_STAGE(bufoff, gbase, voff) do { _Pragma("unroll") for (int _i = 0; _i < 2; ++_i) \
;         __builtin_amdgcn_global_load_lds((const unsigned*)((const char*)(gbase) + (voff)[_i]), (LAS unsigned*)(lds + (bufoff) + ldsw + _i * 8192), 16, 0, 0); } while (0)
; #define PG8_LDA(dst, b, h) do { _Pragma("unroll") for (int m = 0; m < 4; ++m) _Pragma("unroll") for (int k = 0; k < 2; ++k) dst[m][k] = *(const LAS bf16x8*)(lds + PG8_SA(b, h) + aoff + m * 2048 + k * 1024); } while (0)
; #define PG8_MMA(ai, bj, At, Bt) do { __builtin_amdgcn_s_setprio(1); _Pragma("unroll") for (int m = 0; m < 4; ++m) _Pragma("unroll") for (int n = 0; n < 2; ++n) _Pragma("unroll") for (int k = 0; k < 2; ++k) \
;         acc[ai][bj][m][n] = __builtin_amdgcn_mfma_f32_16x16x32_bf16(Bt[n][k], At[m][k], acc[ai][bj][m][n], 0, 0, 0); __builtin_amdgcn_s_setprio(0); } while (0)
; #define PG8_WAIT_V(n) asm volatile("s_waitcnt vmcnt(" #n ")" ::: "memory")
; #define PG8_WAIT_L(n) asm volatile("s_waitcnt lgkmcnt(" #n ")" ::: "memory")
; #define PG8_BAR __builtin_amdgcn_s_barrier()
; #define PG8_SCHED __builtin_amdgcn_sched_barrier(0)
; template <class Epi, class Sched>
; __device__ __forceinline__ void gemm_phase(LAS unsigned char* lds, const int lda, const int ldb, const Sched& S, const Epi& E) {
;     ...
;             PG8_LDA(At, 1, 1); PG8_STAGE(PG8_SB(1, 0), b3, voffB); PG8_STAGE(PG8_SB(1, 1), b3 + hstepB, voffB); PG8_STAGE(PG8_SA(1, 0), a3, voffA);
;             PG8_WAIT_V(8); PG8_WAIT_L(0); PG8_BAR; PG8_MMA(1, 0, At, B0); PG8_MMA(1, 1, At, B1); PG8_BAR; PG8_SCHED;
;         }
	s_add_i32 s22, s58, s26
	v_lshl_add_u64 v[192:193], v[192:193], 0, s[82:83]
	s_mov_b32 m0, s22
	ds_read_b128 v[180:183], v162 offset:49152
	ds_read_b128 v[184:187], v162 offset:50176
	ds_read_b128 v[188:191], v162 offset:51200
	ds_read_b128 v[206:209], v162 offset:52224
	ds_read_b128 v[210:213], v162 offset:53248
	ds_read_b128 v[214:217], v162 offset:54272
	ds_read_b128 v[218:221], v162 offset:55296
	ds_read_b128 v[222:225], v162 offset:56320
	global_load_lds_dwordx4 v[192:193], off
	s_add_i32 m0, s22, 0x2000
	s_add_u32 s22, s44, 0x40080
	v_lshl_add_u64 v[192:193], v[240:241], 0, s[82:83]
	s_addc_u32 s23, s45, 0
	s_add_i32 s44, s59, s26
	global_load_lds_dwordx4 v[192:193], off
	v_lshl_add_u64 v[192:193], s[22:23], 0, v[134:135]
	s_mov_b32 m0, s44
	s_nop 0
	global_load_lds_dwordx4 v[192:193], off
	v_lshl_add_u64 v[192:193], s[22:23], 0, v[130:131]
	s_add_i32 m0, s44, 0x2000
	s_nop 0
	global_load_lds_dwordx4 v[192:193], off
	v_lshl_add_u64 v[192:193], v[242:243], 0, s[82:83]
	s_mov_b32 m0, s50
	s_nop 0
	global_load_lds_dwordx4 v[192:193], off
	v_lshl_add_u64 v[192:193], v[244:245], 0, s[82:83]
	s_mov_b32 m0, s51
	s_nop 0
	global_load_lds_dwordx4 v[192:193], off
	s_waitcnt vmcnt(8)
	s_waitcnt lgkmcnt(0)
	s_barrier
	s_setprio 1
	s_waitcnt lgkmcnt(0)
	v_mfma_f32_16x16x32_bf16 v[62:65], v[142:145], v[180:183], v[62:65]
	v_mfma_f32_16x16x32_bf16 v[58:61], v[150:153], v[180:183], v[58:61]
	v_mfma_f32_16x16x32_bf16 v[54:57], v[142:145], v[188:191], v[54:57]
	v_mfma_f32_16x16x32_bf16 v[46:49], v[150:153], v[188:191], v[46:49]
	v_mfma_f32_16x16x32_bf16 v[38:41], v[142:145], v[210:213], v[38:41]
	v_mfma_f32_16x16x32_bf16 v[30:33], v[150:153], v[210:213], v[30:33]
	v_mfma_f32_16x16x32_bf16 v[22:25], v[142:145], v[218:221], v[22:25]
	v_mfma_f32_16x16x32_bf16 v[14:17], v[150:153], v[218:221], v[14:17]
	v_mfma_f32_16x16x32_bf16 v[62:65], v[146:149], v[184:187], v[62:65]
	v_mfma_f32_16x16x32_bf16 v[58:61], v[154:157], v[184:187], v[58:61]
	v_mfma_f32_16x16x32_bf16 v[54:57], v[146:149], v[206:209], v[54:57]
	v_mfma_f32_16x16x32_bf16 v[46:49], v[154:157], v[206:209], v[46:49]
	v_mfma_f32_16x16x32_bf16 v[38:41], v[146:149], v[214:217], v[38:41]
	v_mfma_f32_16x16x32_bf16 v[30:33], v[154:157], v[214:217], v[30:33]
	v_mfma_f32_16x16x32_bf16 v[22:25], v[146:149], v[222:225], v[22:25]
	v_mfma_f32_16x16x32_bf16 v[14:17], v[154:157], v[222:225], v[14:17]
	s_setprio 0
	s_setprio 1
	v_mfma_f32_16x16x32_bf16 v[50:53], v[164:167], v[180:183], v[50:53]
	v_mfma_f32_16x16x32_bf16 v[42:45], v[172:175], v[180:183], v[42:45]
	v_mfma_f32_16x16x32_bf16 v[34:37], v[164:167], v[188:191], v[34:37]
	v_mfma_f32_16x16x32_bf16 v[26:29], v[172:175], v[188:191], v[26:29]
	v_mfma_f32_16x16x32_bf16 v[18:21], v[164:167], v[210:213], v[18:21]
	v_mfma_f32_16x16x32_bf16 v[10:13], v[172:175], v[210:213], v[10:13]
	v_mfma_f32_16x16x32_bf16 v[6:9], v[164:167], v[218:221], v[6:9]
	v_mfma_f32_16x16x32_bf16 v[2:5], v[172:175], v[218:221], v[2:5]
	v_mfma_f32_16x16x32_bf16 v[50:53], v[168:171], v[184:187], v[50:53]
	v_mfma_f32_16x16x32_bf16 v[42:45], v[176:179], v[184:187], v[42:45]
	v_mfma_f32_16x16x32_bf16 v[34:37], v[168:171], v[206:209], v[34:37]
	v_mfma_f32_16x16x32_bf16 v[26:29], v[176:179], v[206:209], v[26:29]
	v_mfma_f32_16x16x32_bf16 v[18:21], v[168:171], v[214:217], v[18:21]
	v_mfma_f32_16x16x32_bf16 v[10:13], v[176:179], v[214:217], v[10:13]
	v_mfma_f32_16x16x32_bf16 v[6:9], v[168:171], v[222:225], v[6:9]
	v_mfma_f32_16x16x32_bf16 v[2:5], v[176:179], v[222:225], v[2:5]
	s_add_i32 s38, s38, 2
	s_add_u32 s24, s24, 0x100
	s_addc_u32 s25, s25, 0
	s_cmp_gt_u32 s38, 13
	s_mov_b64 s[22:23], s[36:37]
	s_setprio 0
	s_barrier
	s_cbranch_scc0 .LBB0_206
	s_and_b64 vcc, exec, s[10:11]
	s_cbranch_vccz .LBB0_209
	s_barrier

; #define PG8_STAGE(bufoff, gbase, voff) do { _Pragma("unroll") for (int _i = 0; _i < 2; ++_i) \
;         __builtin_amdgcn_global_load_lds((const unsigned*)((const char*)(gbase) + (voff)[_i]), (LAS unsigned*)(lds + (bufoff) + ldsw + _i * 8192), 16, 0, 0); } while (0)
; #define PG8_LDA(dst, b, h) do { _Pragma("unroll") for (int m = 0; m < 4; ++m) _Pragma("unroll") for (int k = 0; k < 2; ++k) dst[m][k] = *(const LAS bf16x8*)(lds + PG8_SA(b, h) + aoff + m * 2048 + k * 1024); } while (0)
; #define PG8_LDB(dst, b, h) do { _Pragma("unroll") for (int n = 0; n < 2; ++n) _Pragma("unroll") for (int k = 0; k < 2; ++k) dst[n][k] = *(const LAS bf16x8*)(lds + PG8_SB(b, h) + boff + n * 2048 + k * 1024); } while (0)
; #define PG8_MMA(ai, bj, At, Bt) do { __builtin_amdgcn_s_setprio(1); _Pragma("unroll") for (int m = 0; m < 4; ++m) _Pragma("unroll") for (int n = 0; n < 2; ++n) _Pragma("unroll") for (int k = 0; k < 2; ++k) \
;         acc[ai][bj][m][n] = __builtin_amdgcn_mfma_f32_16x16x32_bf16(Bt[n][k], At[m][k], acc[ai][bj][m][n], 0, 0, 0); __builtin_amdgcn_s_setprio(0); } while (0)
; #define PG8_WAIT_V(n) asm volatile("s_waitcnt vmcnt(" #n ")" ::: "memory")
; #define PG8_WAIT_L(n) asm volatile("s_waitcnt lgkmcnt(" #n ")" ::: "memory")
; #define PG8_BAR __builtin_amdgcn_s_barrier()
; template <class Epi, class Sched>
; __device__ __forceinline__ void gemm_phase(LAS unsigned char* lds, const int lda, const int ldb, const Sched& S, const Epi& E) {
;     ...
;     for (;;) {
;         const bool has_next = S.next(ui + 1, nxt);
;         const char* nA = has_next ? nxt.A : cA; const char* nB = has_next ? nxt.B : cB;
;         const int nt = cur.nt;
;         for (int t = 0; t < nt; t += 2) {
;             const bool last = (t == nt - 2);
;             const char* a1 = cA + (size_t)(t + 1) * kstep;
;             const char* a2 = last ? nA : cA + (size_t)(t + 2) * kstep; const char* b2 = last ? nB : cB + (size_t)(t + 2) * kstep;
;             const char* a3 = a2 + kstep; const char* b3 = b2 + kstep;
;             PG8_LDB(B0, 0, 0); PG8_LDB(B1, 0, 1); PG8_SCHED; PG8_LDA(At, 0, 0); PG8_STAGE(PG8_SA(1, 1), a1 + hstepA, voffA);
;             PG8_WAIT_V(8); PG8_WAIT_L(0); PG8_BAR; PG8_MMA(0, 0, At, B0); PG8_MMA(0, 1, At, B1); PG8_BAR; PG8_SCHED;
;             PG8_LDA(At, 0, 1); PG8_STAGE(PG8_SB(0, 0), b2, voffB); PG8_STAGE(PG8_SB(0, 1), b2 + hstepB, voffB); PG8_STAGE(PG8_SA(0, 0), a2, voffA);
.LBB0_662:
	s_add_i32 s61, s44, 2
	s_add_u32 s36, s22, 0x100
	s_addc_u32 s37, s23, 0
	s_add_i32 s62, 0, 0x10000
	s_cmp_eq_u32 s24, s44
	s_cselect_b32 s47, s19, s37
	s_cselect_b32 s46, s18, s36
	s_cselect_b32 s45, s21, s60
	s_cselect_b32 s44, s20, s25
	s_add_i32 s63, 0, 0x14000
	v_add_u32_e32 v142, s62, v241
	v_add_u32_e32 v158, s63, v241
	ds_read_b128 v[130:133], v142
	ds_read_b128 v[134:137], v142 offset:1024
	ds_read_b128 v[138:141], v142 offset:2048
	ds_read_b128 v[142:145], v142 offset:3072
	ds_read_b128 v[146:149], v158
	ds_read_b128 v[150:153], v158 offset:1024
	ds_read_b128 v[154:157], v158 offset:2048
	ds_read_b128 v[158:161], v158 offset:3072
	v_lshl_add_u64 v[216:217], s[22:23], 0, v[212:213]
	s_add_i32 m0, s27, 0xc000
	ds_read_b128 v[162:165], v244
	ds_read_b128 v[166:169], v244 offset:1024
	ds_read_b128 v[170:173], v244 offset:2048
	ds_read_b128 v[174:177], v244 offset:3072
	ds_read_b128 v[178:181], v244 offset:4096
	ds_read_b128 v[182:185], v244 offset:5120
	ds_read_b128 v[186:189], v244 offset:6144
	ds_read_b128 v[190:193], v244 offset:7168
	global_load_lds_dwordx4 v[216:217], off
	v_lshl_add_u64 v[216:217], s[22:23], 0, v[214:215]
	s_add_i32 m0, s27, 0xe000
	s_nop 0
	global_load_lds_dwordx4 v[216:217], off
	s_waitcnt vmcnt(8)
	s_waitcnt lgkmcnt(0)
	s_barrier
	s_setprio 1
	s_waitcnt lgkmcnt(0)
	v_mfma_f32_16x16x32_bf16 v[126:129], v[130:133], v[162:165], v[126:129]
	v_mfma_f32_16x16x32_bf16 v[122:125], v[138:141], v[162:165], v[122:125]
	v_mfma_f32_16x16x32_bf16 v[110:113], v[130:133], v[170:173], v[110:113]
	v_mfma_f32_16x16x32_bf16 v[106:109], v[138:141], v[170:173], v[106:109]
	v_mfma_f32_16x16x32_bf16 v[94:97], v[130:133], v[178:181], v[94:97]
	v_mfma_f32_16x16x32_bf16 v[90:93], v[138:141], v[178:181], v[90:93]
	v_mfma_f32_16x16x32_bf16 v[78:81], v[130:133], v[186:189], v[78:81]
	v_mfma_f32_16x16x32_bf16 v[74:77], v[138:141], v[186:189], v[74:77]
	v_mfma_f32_16x16x32_bf16 v[126:129], v[134:137], v[166:169], v[126:129]
	v_mfma_f32_16x16x32_bf16 v[122:125], v[142:145], v[166:169], v[122:125]
	v_mfma_f32_16x16x32_bf16 v[110:113], v[134:137], v[174:177], v[110:113]
	v_mfma_f32_16x16x32_bf16 v[106:109], v[142:145], v[174:177], v[106:109]
	v_mfma_f32_16x16x32_bf16 v[94:97], v[134:137], v[182:185], v[94:97]
	v_mfma_f32_16x16x32_bf16 v[90:93], v[142:145], v[182:185], v[90:93]
	v_mfma_f32_16x16x32_bf16 v[78:81], v[134:137], v[190:193], v[78:81]
	v_mfma_f32_16x16x32_bf16 v[74:77], v[142:145], v[190:193], v[74:77]
	s_setprio 0
	s_setprio 1
	v_mfma_f32_16x16x32_bf16 v[118:121], v[146:149], v[162:165], v[118:121]
	v_mfma_f32_16x16x32_bf16 v[114:117], v[154:157], v[162:165], v[114:117]
	v_mfma_f32_16x16x32_bf16 v[102:105], v[146:149], v[170:173], v[102:105]
	v_mfma_f32_16x16x32_bf16 v[98:101], v[154:157], v[170:173], v[98:101]
	v_mfma_f32_16x16x32_bf16 v[86:89], v[146:149], v[178:181], v[86:89]
	v_mfma_f32_16x16x32_bf16 v[82:85], v[154:157], v[178:181], v[82:85]
	v_mfma_f32_16x16x32_bf16 v[70:73], v[146:149], v[186:189], v[70:73]
	v_mfma_f32_16x16x32_bf16 v[66:69], v[154:157], v[186:189], v[66:69]
	v_mfma_f32_16x16x32_bf16 v[118:121], v[150:153], v[166:169], v[118:121]
	v_mfma_f32_16x16x32_bf16 v[114:117], v[158:161], v[166:169], v[114:117]
	v_mfma_f32_16x16x32_bf16 v[102:105], v[150:153], v[174:177], v[102:105]
	v_mfma_f32_16x16x32_bf16 v[98:101], v[158:161], v[174:177], v[98:101]
	v_mfma_f32_16x16x32_bf16 v[86:89], v[150:153], v[182:185], v[86:89]
	v_mfma_f32_16x16x32_bf16 v[82:85], v[158:161], v[182:185], v[82:85]
	v_mfma_f32_16x16x32_bf16 v[70:73], v[150:153], v[190:193], v[70:73]
	v_mfma_f32_16x16x32_bf16 v[66:69], v[158:161], v[190:193], v[66:69]
	s_setprio 0
	s_barrier
	s_add_i32 s22, s62, s26
	v_lshl_add_u64 v[216:217], s[44:45], 0, v[0:1]
	s_mov_b32 m0, s22
	ds_read_b128 v[162:165], v244 offset:16384
	ds_read_b128 v[166:169], v244 offset:17408
	ds_read_b128 v[170:173], v244 offset:18432
	ds_read_b128 v[174:177], v244 offset:19456
	ds_read_b128 v[178:181], v244 offset:20480
	ds_read_b128 v[182:185], v244 offset:21504
	ds_read_b128 v[186:189], v244 offset:22528
	ds_read_b128 v[190:193], v244 offset:23552
	global_load_lds_dwordx4 v[216:217], off
	s_add_i32 m0, s22, 0x2000
	s_add_u32 s22, s44, 0x40000
	v_lshl_add_u64 v[218:219], s[44:45], 0, v[210:211]
	s_addc_u32 s23, s45, 0
	s_add_i32 s62, s63, s26
	global_load_lds_dwordx4 v[218:219], off
	v_lshl_add_u64 v[220:221], s[22:23], 0, v[0:1]
	s_mov_b32 m0, s62
	v_lshl_add_u64 v[222:223], s[46:47], 0, v[208:209]
	global_load_lds_dwordx4 v[220:221], off
	v_lshl_add_u64 v[220:221], s[22:23], 0, v[210:211]
	s_add_i32 m0, s62, 0x2000
	s_nop 0
	global_load_lds_dwordx4 v[220:221], off
	v_lshl_add_u64 v[220:221], s[46:47], 0, v[206:207]
	s_mov_b32 m0, s27
	s_nop 0
	global_load_lds_dwordx4 v[220:221], off
	s_mov_b32 m0, s28
	s_nop 0
	global_load_lds_dwordx4 v[222:223], off
	s_waitcnt vmcnt(8)
	s_waitcnt lgkmcnt(0)
	s_barrier
; #define PG8_STAGE(bufoff, gbase, voff) do { _Pragma("unroll") for (int _i = 0; _i < 2; ++_i) \
;         __builtin_amdgcn_global_load_lds((const unsigned*)((const char*)(gbase) + (voff)[_i]), (LAS unsigned*)(lds + (bufoff) + ldsw + _i * 8192), 16, 0, 0); } while (0)
; #define PG8_LDA(dst, b, h) do { _Pragma("unroll") for (int m = 0; m < 4; ++m) _Pragma("unroll") for (int k = 0; k < 2; ++k) dst[m][k] = *(const LAS bf16x8*)(lds + PG8_SA(b, h) + aoff + m * 2048 + k * 1024); } while (0)
; #define PG8_LDB(dst, b, h) do { _Pragma("unroll") for (int n = 0; n < 2; ++n) _Pragma("unroll") for (int k = 0; k < 2; ++k) dst[n][k] = *(const LAS bf16x8*)(lds + PG8_SB(b, h) + boff + n * 2048 + k * 1024); } while (0)
; #define PG8_MMA(ai, bj, At, Bt) do { __builtin_amdgcn_s_setprio(1); _Pragma("unroll") for (int m = 0; m < 4; ++m) _Pragma("unroll") for (int n = 0; n < 2; ++n) _Pragma("unroll") for (int k = 0; k < 2; ++k) \
;         acc[ai][bj][m][n] = __builtin_amdgcn_mfma_f32_16x16x32_bf16(Bt[n][k], At[m][k], acc[ai][bj][m][n], 0, 0, 0); __builtin_amdgcn_s_setprio(0); } while (0)
; #define PG8_WAIT_V(n) asm volatile("s_waitcnt vmcnt(" #n ")" ::: "memory")
; #define PG8_WAIT_L(n) asm volatile("s_waitcnt lgkmcnt(" #n ")" ::: "memory")
; #define PG8_BAR __builtin_amdgcn_s_barrier()
; #define PG8_SCHED __builtin_amdgcn_sched_barrier(0)
; template <class Epi, class Sched>
; __device__ __forceinline__ void gemm_phase(LAS unsigned char* lds, const int lda, const int ldb, const Sched& S, const Epi& E) {
;     ...
;             PG8_WAIT_V(8); PG8_WAIT_L(0); PG8_BAR; PG8_MMA(1, 0, At, B0); PG8_MMA(1, 1, At, B1); PG8_BAR; PG8_SCHED;
;             PG8_LDB(B0, 1, 0); PG8_LDB(B1, 1, 1); PG8_SCHED; PG8_LDA(At, 1, 0); PG8_STAGE(PG8_SA(0, 1), a2 + hstepA, voffA);
;             PG8_WAIT_V(8); PG8_WAIT_L(0); PG8_BAR; PG8_MMA(0, 0, At, B0); PG8_MMA(0, 1, At, B1); PG8_BAR; PG8_SCHED;
	s_setprio 1
	s_waitcnt lgkmcnt(0)
	v_mfma_f32_16x16x32_bf16 v[62:65], v[130:133], v[162:165], v[62:65]
	v_mfma_f32_16x16x32_bf16 v[58:61], v[138:141], v[162:165], v[58:61]
	v_mfma_f32_16x16x32_bf16 v[46:49], v[130:133], v[170:173], v[46:49]
	v_mfma_f32_16x16x32_bf16 v[42:45], v[138:141], v[170:173], v[42:45]
	v_mfma_f32_16x16x32_bf16 v[30:33], v[130:133], v[178:181], v[30:33]
	v_mfma_f32_16x16x32_bf16 v[26:29], v[138:141], v[178:181], v[26:29]
	v_mfma_f32_16x16x32_bf16 v[14:17], v[130:133], v[186:189], v[14:17]
	v_mfma_f32_16x16x32_bf16 v[10:13], v[138:141], v[186:189], v[10:13]
	v_mfma_f32_16x16x32_bf16 v[62:65], v[134:137], v[166:169], v[62:65]
	v_mfma_f32_16x16x32_bf16 v[58:61], v[142:145], v[166:169], v[58:61]
	v_mfma_f32_16x16x32_bf16 v[46:49], v[134:137], v[174:177], v[46:49]
	v_mfma_f32_16x16x32_bf16 v[42:45], v[142:145], v[174:177], v[42:45]
	v_mfma_f32_16x16x32_bf16 v[30:33], v[134:137], v[182:185], v[30:33]
	v_mfma_f32_16x16x32_bf16 v[26:29], v[142:145], v[182:185], v[26:29]
	v_mfma_f32_16x16x32_bf16 v[14:17], v[134:137], v[190:193], v[14:17]
	v_mfma_f32_16x16x32_bf16 v[10:13], v[142:145], v[190:193], v[10:13]
	s_setprio 0
	s_setprio 1
	v_mfma_f32_16x16x32_bf16 v[54:57], v[146:149], v[162:165], v[54:57]
	v_mfma_f32_16x16x32_bf16 v[50:53], v[154:157], v[162:165], v[50:53]
	v_mfma_f32_16x16x32_bf16 v[38:41], v[146:149], v[170:173], v[38:41]
	v_mfma_f32_16x16x32_bf16 v[34:37], v[154:157], v[170:173], v[34:37]
	v_mfma_f32_16x16x32_bf16 v[22:25], v[146:149], v[178:181], v[22:25]
	v_mfma_f32_16x16x32_bf16 v[18:21], v[154:157], v[178:181], v[18:21]
	v_mfma_f32_16x16x32_bf16 v[6:9], v[146:149], v[186:189], v[6:9]
	v_mfma_f32_16x16x32_bf16 v[2:5], v[154:157], v[186:189], v[2:5]
	v_mfma_f32_16x16x32_bf16 v[54:57], v[150:153], v[166:169], v[54:57]
	v_mfma_f32_16x16x32_bf16 v[50:53], v[158:161], v[166:169], v[50:53]
	v_mfma_f32_16x16x32_bf16 v[38:41], v[150:153], v[174:177], v[38:41]
	v_mfma_f32_16x16x32_bf16 v[34:37], v[158:161], v[174:177], v[34:37]
	v_mfma_f32_16x16x32_bf16 v[22:25], v[150:153], v[182:185], v[22:25]
	v_mfma_f32_16x16x32_bf16 v[18:21], v[158:161], v[182:185], v[18:21]
	v_mfma_f32_16x16x32_bf16 v[6:9], v[150:153], v[190:193], v[6:9]
	v_mfma_f32_16x16x32_bf16 v[2:5], v[158:161], v[190:193], v[2:5]
	s_setprio 0
	s_barrier
	s_add_i32 s62, 0, 0x18000
	s_add_i32 s63, 0, 0x1c000
	v_add_u32_e32 v142, s62, v241
	v_add_u32_e32 v158, s63, v241
	ds_read_b128 v[130:133], v142
	ds_read_b128 v[134:137], v142 offset:1024
	ds_read_b128 v[138:141], v142 offset:2048
	ds_read_b128 v[142:145], v142 offset:3072
	ds_read_b128 v[146:149], v158
	ds_read_b128 v[150:153], v158 offset:1024
	ds_read_b128 v[154:157], v158 offset:2048
	ds_read_b128 v[158:161], v158 offset:3072
	s_add_u32 s22, s46, 0x190000
	s_addc_u32 s23, s47, 0
	s_mov_b32 m0, s29
	v_lshl_add_u64 v[224:225], s[22:23], 0, v[206:207]
	ds_read_b128 v[162:165], v244 offset:32768
	ds_read_b128 v[166:169], v244 offset:33792
	ds_read_b128 v[170:173], v244 offset:34816
	ds_read_b128 v[174:177], v244 offset:35840
	ds_read_b128 v[178:181], v244 offset:36864
	ds_read_b128 v[182:185], v244 offset:37888
	ds_read_b128 v[186:189], v244 offset:38912
	ds_read_b128 v[190:193], v244 offset:39936
	global_load_lds_dwordx4 v[224:225], off
	v_lshl_add_u64 v[224:225], s[22:23], 0, v[208:209]
	s_mov_b32 m0, s33
	s_nop 0
	global_load_lds_dwordx4 v[224:225], off
	s_waitcnt vmcnt(8)
	s_waitcnt lgkmcnt(0)
	s_barrier
	s_setprio 1
	s_waitcnt lgkmcnt(0)
	v_mfma_f32_16x16x32_bf16 v[126:129], v[130:133], v[162:165], v[126:129]
	v_mfma_f32_16x16x32_bf16 v[122:125], v[138:141], v[162:165], v[122:125]
	v_mfma_f32_16x16x32_bf16 v[110:113], v[130:133], v[170:173], v[110:113]
	v_mfma_f32_16x16x32_bf16 v[106:109], v[138:141], v[170:173], v[106:109]
	v_mfma_f32_16x16x32_bf16 v[94:97], v[130:133], v[178:181], v[94:97]
	v_mfma_f32_16x16x32_bf16 v[90:93], v[138:141], v[178:181], v[90:93]
	v_mfma_f32_16x16x32_bf16 v[78:81], v[130:133], v[186:189], v[78:81]
	v_mfma_f32_16x16x32_bf16 v[74:77], v[138:141], v[186:189], v[74:77]
	v_mfma_f32_16x16x32_bf16 v[126:129], v[134:137], v[166:169], v[126:129]
	v_mfma_f32_16x16x32_bf16 v[122:125], v[142:145], v[166:169], v[122:125]
	v_mfma_f32_16x16x32_bf16 v[110:113], v[134:137], v[174:177], v[110:113]
	v_mfma_f32_16x16x32_bf16 v[106:109], v[142:145], v[174:177], v[106:109]
	v_mfma_f32_16x16x32_bf16 v[94:97], v[134:137], v[182:185], v[94:97]
	v_mfma_f32_16x16x32_bf16 v[90:93], v[142:145], v[182:185], v[90:93]
	v_mfma_f32_16x16x32_bf16 v[78:81], v[134:137], v[190:193], v[78:81]
	v_mfma_f32_16x16x32_bf16 v[74:77], v[142:145], v[190:193], v[74:77]
	s_setprio 0
	s_setprio 1
	v_mfma_f32_16x16x32_bf16 v[118:121], v[146:149], v[162:165], v[118:121]
	v_mfma_f32_16x16x32_bf16 v[114:117], v[154:157], v[162:165], v[114:117]
	v_mfma_f32_16x16x32_bf16 v[102:105], v[146:149], v[170:173], v[102:105]
	v_mfma_f32_16x16x32_bf16 v[98:101], v[154:157], v[170:173], v[98:101]
	v_mfma_f32_16x16x32_bf16 v[86:89], v[146:149], v[178:181], v[86:89]
	v_mfma_f32_16x16x32_bf16 v[82:85], v[154:157], v[178:181], v[82:85]
	v_mfma_f32_16x16x32_bf16 v[70:73], v[146:149], v[186:189], v[70:73]
	v_mfma_f32_16x16x32_bf16 v[66:69], v[154:157], v[186:189], v[66:69]
	v_mfma_f32_16x16x32_bf16 v[118:121], v[150:153], v[166:169], v[118:121]
	v_mfma_f32_16x16x32_bf16 v[114:117], v[158:161], v[166:169], v[114:117]
	v_mfma_f32_16x16x32_bf16 v[102:105], v[150:153], v[174:177], v[102:105]
	v_mfma_f32_16x16x32_bf16 v[98:101], v[158:161], v[174:177], v[98:101]
	v_mfma_f32_16x16x32_bf16 v[86:89], v[150:153], v[182:185], v[86:89]
	v_mfma_f32_16x16x32_bf16 v[82:85], v[158:161], v[182:185], v[82:85]
	v_mfma_f32_16x16x32_bf16 v[70:73], v[150:153], v[190:193], v[70:73]
	v_mfma_f32_16x16x32_bf16 v[66:69], v[158:161], v[190:193], v[66:69]
	s_setprio 0
	s_barrier
; #define PG8_STAGE(bufoff, gbase, voff) do { _Pragma("unroll") for (int _i = 0; _i < 2; ++_i) \
;         __builtin_amdgcn_global_load_lds((const unsigned*)((const char*)(gbase) + (voff)[_i]), (LAS unsigned*)(lds + (bufoff) + ldsw + _i * 8192), 16, 0, 0); } while (0)
; #define PG8_LDA(dst, b, h) do { _Pragma("unroll") for (int m = 0; m < 4; ++m) _Pragma("unroll") for (int k = 0; k < 2; ++k) dst[m][k] = *(const LAS bf16x8*)(lds + PG8_SA(b, h) + aoff + m * 2048 + k * 1024); } while (0)
; #define PG8_MMA(ai, bj, At, Bt) do { __builtin_amdgcn_s_setprio(1); _Pragma("unroll") for (int m = 0; m < 4; ++m) _Pragma("unroll") for (int n = 0; n < 2; ++n) _Pragma("unroll") for (int k = 0; k < 2; ++k) \
;         acc[ai][bj][m][n] = __builtin_amdgcn_mfma_f32_16x16x32_bf16(Bt[n][k], At[m][k], acc[ai][bj][m][n], 0, 0, 0); __builtin_amdgcn_s_setprio(0); } while (0)
; #define PG8_WAIT_V(n) asm volatile("s_waitcnt vmcnt(" #n ")" ::: "memory")
; #define PG8_WAIT_L(n) asm volatile("s_waitcnt lgkmcnt(" #n ")" ::: "memory")
; #define PG8_BAR __builtin_amdgcn_s_barrier()
; #define PG8_SCHED __builtin_amdgcn_sched_barrier(0)
; template <class Epi, class Sched>
; __device__ __forceinline__ void gemm_phase(LAS unsigned char* lds, const int lda, const int ldb, const Sched& S, const Epi& E) {
;     ...
;         for (int t = 0; t < nt; t += 2) {
;     ...
;             PG8_LDA(At, 1, 1); PG8_STAGE(PG8_SB(1, 0), b3, voffB); PG8_STAGE(PG8_SB(1, 1), b3 + hstepB, voffB); PG8_STAGE(PG8_SA(1, 0), a3, voffA);
;             PG8_WAIT_V(8); PG8_WAIT_L(0); PG8_BAR; PG8_MMA(1, 0, At, B0); PG8_MMA(1, 1, At, B1); PG8_BAR; PG8_SCHED;
;         }
	s_add_i32 s22, s62, s26
	v_lshl_add_u64 v[216:217], v[216:217], 0, s[82:83]
	s_mov_b32 m0, s22
	ds_read_b128 v[162:165], v244 offset:49152
	ds_read_b128 v[166:169], v244 offset:50176
	ds_read_b128 v[170:173], v244 offset:51200
	ds_read_b128 v[174:177], v244 offset:52224
	ds_read_b128 v[178:181], v244 offset:53248
	ds_read_b128 v[182:185], v244 offset:54272
	ds_read_b128 v[186:189], v244 offset:55296
	ds_read_b128 v[190:193], v244 offset:56320
	global_load_lds_dwordx4 v[216:217], off
	s_add_i32 m0, s22, 0x2000
	s_add_u32 s22, s44, 0x40080
	v_lshl_add_u64 v[216:217], v[218:219], 0, s[82:83]
	s_addc_u32 s23, s45, 0
	s_add_i32 s44, s63, s26
	global_load_lds_dwordx4 v[216:217], off
	v_lshl_add_u64 v[216:217], s[22:23], 0, v[0:1]
	s_mov_b32 m0, s44
	s_nop 0
	global_load_lds_dwordx4 v[216:217], off
	v_lshl_add_u64 v[216:217], s[22:23], 0, v[210:211]
	s_add_i32 m0, s44, 0x2000
	s_nop 0
	global_load_lds_dwordx4 v[216:217], off
	v_lshl_add_u64 v[216:217], v[220:221], 0, s[82:83]
	s_mov_b32 m0, s38
	s_nop 0
	global_load_lds_dwordx4 v[216:217], off
	v_lshl_add_u64 v[216:217], v[222:223], 0, s[82:83]
	s_mov_b32 m0, s48
	s_nop 0
	global_load_lds_dwordx4 v[216:217], off
	s_waitcnt vmcnt(8)
	s_waitcnt lgkmcnt(0)
	s_barrier
	s_setprio 1
	s_waitcnt lgkmcnt(0)
	v_mfma_f32_16x16x32_bf16 v[62:65], v[130:133], v[162:165], v[62:65]
	v_mfma_f32_16x16x32_bf16 v[58:61], v[138:141], v[162:165], v[58:61]
	v_mfma_f32_16x16x32_bf16 v[46:49], v[130:133], v[170:173], v[46:49]
	v_mfma_f32_16x16x32_bf16 v[42:45], v[138:141], v[170:173], v[42:45]
	v_mfma_f32_16x16x32_bf16 v[30:33], v[130:133], v[178:181], v[30:33]
	v_mfma_f32_16x16x32_bf16 v[26:29], v[138:141], v[178:181], v[26:29]
	v_mfma_f32_16x16x32_bf16 v[14:17], v[130:133], v[186:189], v[14:17]
	v_mfma_f32_16x16x32_bf16 v[10:13], v[138:141], v[186:189], v[10:13]
	v_mfma_f32_16x16x32_bf16 v[62:65], v[134:137], v[166:169], v[62:65]
	v_mfma_f32_16x16x32_bf16 v[58:61], v[142:145], v[166:169], v[58:61]
	v_mfma_f32_16x16x32_bf16 v[46:49], v[134:137], v[174:177], v[46:49]
	v_mfma_f32_16x16x32_bf16 v[42:45], v[142:145], v[174:177], v[42:45]
	v_mfma_f32_16x16x32_bf16 v[30:33], v[134:137], v[182:185], v[30:33]
	v_mfma_f32_16x16x32_bf16 v[26:29], v[142:145], v[182:185], v[26:29]
	v_mfma_f32_16x16x32_bf16 v[14:17], v[134:137], v[190:193], v[14:17]
	v_mfma_f32_16x16x32_bf16 v[10:13], v[142:145], v[190:193], v[10:13]
	s_setprio 0
	s_setprio 1
	v_mfma_f32_16x16x32_bf16 v[54:57], v[146:149], v[162:165], v[54:57]
	v_mfma_f32_16x16x32_bf16 v[50:53], v[154:157], v[162:165], v[50:53]
	v_mfma_f32_16x16x32_bf16 v[38:41], v[146:149], v[170:173], v[38:41]
	v_mfma_f32_16x16x32_bf16 v[34:37], v[154:157], v[170:173], v[34:37]
	v_mfma_f32_16x16x32_bf16 v[22:25], v[146:149], v[178:181], v[22:25]
	v_mfma_f32_16x16x32_bf16 v[18:21], v[154:157], v[178:181], v[18:21]
	v_mfma_f32_16x16x32_bf16 v[6:9], v[146:149], v[186:189], v[6:9]
	v_mfma_f32_16x16x32_bf16 v[2:5], v[154:157], v[186:189], v[2:5]
	v_mfma_f32_16x16x32_bf16 v[54:57], v[150:153], v[166:169], v[54:57]
	v_mfma_f32_16x16x32_bf16 v[50:53], v[158:161], v[166:169], v[50:53]
	v_mfma_f32_16x16x32_bf16 v[38:41], v[150:153], v[174:177], v[38:41]
	v_mfma_f32_16x16x32_bf16 v[34:37], v[158:161], v[174:177], v[34:37]
	v_mfma_f32_16x16x32_bf16 v[22:25], v[150:153], v[182:185], v[22:25]
	v_mfma_f32_16x16x32_bf16 v[18:21], v[158:161], v[182:185], v[18:21]
	v_mfma_f32_16x16x32_bf16 v[6:9], v[150:153], v[190:193], v[6:9]
	v_mfma_f32_16x16x32_bf16 v[2:5], v[158:161], v[190:193], v[2:5]
	s_add_u32 s25, s25, 0x100
	s_addc_u32 s60, s60, 0
	s_cmp_ge_i32 s61, s59
	s_mov_b64 s[22:23], s[36:37]
	s_mov_b32 s44, s61
	s_setprio 0
	s_barrier
	s_cbranch_scc0 .LBB0_662
	s_and_b64 vcc, exec, s[14:15]
	s_cbranch_vccz .LBB0_665
	s_barrier

; #define PG8_STAGE(bufoff, gbase, voff) do { _Pragma("unroll") for (int _i = 0; _i < 2; ++_i) \
;         __builtin_amdgcn_global_load_lds((const unsigned*)((const char*)(gbase) + (voff)[_i]), (LAS unsigned*)(lds + (bufoff) + ldsw + _i * 8192), 16, 0, 0); } while (0)
; #define PG8_LDA(dst, b, h) do { _Pragma("unroll") for (int m = 0; m < 4; ++m) _Pragma("unroll") for (int k = 0; k < 2; ++k) dst[m][k] = *(const LAS bf16x8*)(lds + PG8_SA(b, h) + aoff + m * 2048 + k * 1024); } while (0)
; #define PG8_LDB(dst, b, h) do { _Pragma("unroll") for (int n = 0; n < 2; ++n) _Pragma("unroll") for (int k = 0; k < 2; ++k) dst[n][k] = *(const LAS bf16x8*)(lds + PG8_SB(b, h) + boff + n * 2048 + k * 1024); } while (0)
; #define PG8_MMA(ai, bj, At, Bt) do { __builtin_amdgcn_s_setprio(1); _Pragma("unroll") for (int m = 0; m < 4; ++m) _Pragma("unroll") for (int n = 0; n < 2; ++n) _Pragma("unroll") for (int k = 0; k < 2; ++k) \
;         acc[ai][bj][m][n] = __builtin_amdgcn_mfma_f32_16x16x32_bf16(Bt[n][k], At[m][k], acc[ai][bj][m][n], 0, 0, 0); __builtin_amdgcn_s_setprio(0); } while (0)
; #define PG8_WAIT_V(n) asm volatile("s_waitcnt vmcnt(" #n ")" ::: "memory")
; #define PG8_WAIT_L(n) asm volatile("s_waitcnt lgkmcnt(" #n ")" ::: "memory")
; #define PG8_BAR __builtin_amdgcn_s_barrier()
; #define PG8_SCHED __builtin_amdgcn_sched_barrier(0)
; template <class Epi, class Sched>
; __device__ __forceinline__ void gemm_phase(LAS unsigned char* lds, const int lda, const int ldb, const Sched& S, const Epi& E) {
;     ...
;             const bool last = (t == nt - 2);
;             const char* a1 = cA + (size_t)(t + 1) * kstep;
;             const char* a2 = last ? nA : cA + (size_t)(t + 2) * kstep; const char* b2 = last ? nB : cB + (size_t)(t + 2) * kstep;
;             const char* a3 = a2 + kstep; const char* b3 = b2 + kstep;
;             PG8_LDB(B0, 0, 0); PG8_LDB(B1, 0, 1); PG8_SCHED; PG8_LDA(At, 0, 0); PG8_STAGE(PG8_SA(1, 1), a1 + hstepA, voffA);
;             PG8_WAIT_V(8); PG8_WAIT_L(0); PG8_BAR; PG8_MMA(0, 0, At, B0); PG8_MMA(0, 1, At, B1); PG8_BAR; PG8_SCHED;
;             PG8_LDA(At, 0, 1); PG8_STAGE(PG8_SB(0, 0), b2, voffB); PG8_STAGE(PG8_SB(0, 1), b2 + hstepB, voffB); PG8_STAGE(PG8_SA(0, 0), a2, voffA);
.LBB0_802:
	s_add_u32 s36, s22, 0x100
	s_addc_u32 s37, s23, 0
	s_add_i32 s56, 0, 0x10000
	s_cmp_eq_u32 s25, 12
	s_cselect_b32 s47, s19, s37
	s_cselect_b32 s46, s18, s36
	v_add_u32_e32 v148, s56, v151
	s_cselect_b32 s45, s21, s24
	s_cselect_b32 s44, s20, s17
	s_add_i32 s57, 0, 0x14000
	ds_read_b128 v[140:143], v148
	ds_read_b128 v[144:147], v148 offset:1024
	ds_read_b128 v[154:157], v148 offset:2048
	ds_read_b128 v[158:161], v148 offset:3072
	v_add_u32_e32 v148, s57, v151
	ds_read_b128 v[162:165], v148
	ds_read_b128 v[166:169], v148 offset:1024
	ds_read_b128 v[170:173], v148 offset:2048
	ds_read_b128 v[174:177], v148 offset:3072
	v_lshl_add_u64 v[148:149], s[22:23], 0, v[136:137]
	s_add_i32 m0, s29, 0xc000
	ds_read_b128 v[178:181], v153
	ds_read_b128 v[182:185], v153 offset:1024
	ds_read_b128 v[186:189], v153 offset:2048
	ds_read_b128 v[190:193], v153 offset:3072
	ds_read_b128 v[206:209], v153 offset:4096
	ds_read_b128 v[210:213], v153 offset:5120
	ds_read_b128 v[214:217], v153 offset:6144
	ds_read_b128 v[218:221], v153 offset:7168
	global_load_lds_dwordx4 v[148:149], off
	v_lshl_add_u64 v[148:149], s[22:23], 0, v[138:139]
	s_add_i32 m0, s29, 0xe000
	s_nop 0
	global_load_lds_dwordx4 v[148:149], off
	s_waitcnt vmcnt(8)
	s_waitcnt lgkmcnt(0)
	s_barrier
	s_setprio 1
	s_waitcnt lgkmcnt(0)
	v_mfma_f32_16x16x32_bf16 v[126:129], v[140:143], v[178:181], v[126:129]
	v_mfma_f32_16x16x32_bf16 v[122:125], v[154:157], v[178:181], v[122:125]
	v_mfma_f32_16x16x32_bf16 v[110:113], v[140:143], v[186:189], v[110:113]
	v_mfma_f32_16x16x32_bf16 v[106:109], v[154:157], v[186:189], v[106:109]
	v_mfma_f32_16x16x32_bf16 v[94:97], v[140:143], v[206:209], v[94:97]
	v_mfma_f32_16x16x32_bf16 v[90:93], v[154:157], v[206:209], v[90:93]
	v_mfma_f32_16x16x32_bf16 v[78:81], v[140:143], v[214:217], v[78:81]
	v_mfma_f32_16x16x32_bf16 v[74:77], v[154:157], v[214:217], v[74:77]
	v_mfma_f32_16x16x32_bf16 v[126:129], v[144:147], v[182:185], v[126:129]
	v_mfma_f32_16x16x32_bf16 v[122:125], v[158:161], v[182:185], v[122:125]
	v_mfma_f32_16x16x32_bf16 v[110:113], v[144:147], v[190:193], v[110:113]
	v_mfma_f32_16x16x32_bf16 v[106:109], v[158:161], v[190:193], v[106:109]
	v_mfma_f32_16x16x32_bf16 v[94:97], v[144:147], v[210:213], v[94:97]
	v_mfma_f32_16x16x32_bf16 v[90:93], v[158:161], v[210:213], v[90:93]
	v_mfma_f32_16x16x32_bf16 v[78:81], v[144:147], v[218:221], v[78:81]
	v_mfma_f32_16x16x32_bf16 v[74:77], v[158:161], v[218:221], v[74:77]
	s_setprio 0
	s_setprio 1
	v_mfma_f32_16x16x32_bf16 v[118:121], v[162:165], v[178:181], v[118:121]
	v_mfma_f32_16x16x32_bf16 v[114:117], v[170:173], v[178:181], v[114:117]
	v_mfma_f32_16x16x32_bf16 v[102:105], v[162:165], v[186:189], v[102:105]
	v_mfma_f32_16x16x32_bf16 v[98:101], v[170:173], v[186:189], v[98:101]
	v_mfma_f32_16x16x32_bf16 v[86:89], v[162:165], v[206:209], v[86:89]
	v_mfma_f32_16x16x32_bf16 v[82:85], v[170:173], v[206:209], v[82:85]
	v_mfma_f32_16x16x32_bf16 v[70:73], v[162:165], v[214:217], v[70:73]
	v_mfma_f32_16x16x32_bf16 v[66:69], v[170:173], v[214:217], v[66:69]
	v_mfma_f32_16x16x32_bf16 v[118:121], v[166:169], v[182:185], v[118:121]
	v_mfma_f32_16x16x32_bf16 v[114:117], v[174:177], v[182:185], v[114:117]
	v_mfma_f32_16x16x32_bf16 v[102:105], v[166:169], v[190:193], v[102:105]
	v_mfma_f32_16x16x32_bf16 v[98:101], v[174:177], v[190:193], v[98:101]
	v_mfma_f32_16x16x32_bf16 v[86:89], v[166:169], v[210:213], v[86:89]
	v_mfma_f32_16x16x32_bf16 v[82:85], v[174:177], v[210:213], v[82:85]
	v_mfma_f32_16x16x32_bf16 v[70:73], v[166:169], v[218:221], v[70:73]
	v_mfma_f32_16x16x32_bf16 v[66:69], v[174:177], v[218:221], v[66:69]
	s_setprio 0
	s_barrier
	s_add_i32 s22, s56, s28
	v_lshl_add_u64 v[148:149], s[44:45], 0, v[0:1]
	s_mov_b32 m0, s22
	ds_read_b128 v[178:181], v153 offset:16384
	ds_read_b128 v[182:185], v153 offset:17408
	ds_read_b128 v[186:189], v153 offset:18432
	ds_read_b128 v[190:193], v153 offset:19456
	ds_read_b128 v[206:209], v153 offset:20480
	ds_read_b128 v[210:213], v153 offset:21504
	ds_read_b128 v[214:217], v153 offset:22528
	ds_read_b128 v[218:221], v153 offset:23552
	global_load_lds_dwordx4 v[148:149], off
	s_add_i32 m0, s22, 0x2000
	s_add_u32 s22, s44, 0x40000
	v_lshl_add_u64 v[222:223], s[44:45], 0, v[134:135]
	s_addc_u32 s23, s45, 0
	s_add_i32 s56, s57, s28
	global_load_lds_dwordx4 v[222:223], off
	v_lshl_add_u64 v[224:225], s[22:23], 0, v[0:1]
	s_mov_b32 m0, s56
	v_lshl_add_u64 v[240:241], s[46:47], 0, v[132:133]
	global_load_lds_dwordx4 v[224:225], off
	v_lshl_add_u64 v[224:225], s[22:23], 0, v[134:135]
	s_add_i32 m0, s56, 0x2000
	s_nop 0
	global_load_lds_dwordx4 v[224:225], off
	v_lshl_add_u64 v[224:225], s[46:47], 0, v[130:131]
	s_mov_b32 m0, s29
	s_nop 0
	global_load_lds_dwordx4 v[224:225], off
	s_mov_b32 m0, s33
	s_nop 0
	global_load_lds_dwordx4 v[240:241], off
	s_waitcnt vmcnt(8)
	s_waitcnt lgkmcnt(0)
	s_barrier
; #define PG8_STAGE(bufoff, gbase, voff) do { _Pragma("unroll") for (int _i = 0; _i < 2; ++_i) \
;         __builtin_amdgcn_global_load_lds((const unsigned*)((const char*)(gbase) + (voff)[_i]), (LAS unsigned*)(lds + (bufoff) + ldsw + _i * 8192), 16, 0, 0); } while (0)
; #define PG8_LDA(dst, b, h) do { _Pragma("unroll") for (int m = 0; m < 4; ++m) _Pragma("unroll") for (int k = 0; k < 2; ++k) dst[m][k] = *(const LAS bf16x8*)(lds + PG8_SA(b, h) + aoff + m * 2048 + k * 1024); } while (0)
; #define PG8_LDB(dst, b, h) do { _Pragma("unroll") for (int n = 0; n < 2; ++n) _Pragma("unroll") for (int k = 0; k < 2; ++k) dst[n][k] = *(const LAS bf16x8*)(lds + PG8_SB(b, h) + boff + n * 2048 + k * 1024); } while (0)
; #define PG8_MMA(ai, bj, At, Bt) do { __builtin_amdgcn_s_setprio(1); _Pragma("unroll") for (int m = 0; m < 4; ++m) _Pragma("unroll") for (int n = 0; n < 2; ++n) _Pragma("unroll") for (int k = 0; k < 2; ++k) \
;         acc[ai][bj][m][n] = __builtin_amdgcn_mfma_f32_16x16x32_bf16(Bt[n][k], At[m][k], acc[ai][bj][m][n], 0, 0, 0); __builtin_amdgcn_s_setprio(0); } while (0)
; #define PG8_WAIT_V(n) asm volatile("s_waitcnt vmcnt(" #n ")" ::: "memory")
; #define PG8_WAIT_L(n) asm volatile("s_waitcnt lgkmcnt(" #n ")" ::: "memory")
; #define PG8_BAR __builtin_amdgcn_s_barrier()
; #define PG8_SCHED __builtin_amdgcn_sched_barrier(0)
; template <class Epi, class Sched>
; __device__ __forceinline__ void gemm_phase(LAS unsigned char* lds, const int lda, const int ldb, const Sched& S, const Epi& E) {
;     ...
;             PG8_WAIT_V(8); PG8_WAIT_L(0); PG8_BAR; PG8_MMA(1, 0, At, B0); PG8_MMA(1, 1, At, B1); PG8_BAR; PG8_SCHED;
;             PG8_LDB(B0, 1, 0); PG8_LDB(B1, 1, 1); PG8_SCHED; PG8_LDA(At, 1, 0); PG8_STAGE(PG8_SA(0, 1), a2 + hstepA, voffA);
;             PG8_WAIT_V(8); PG8_WAIT_L(0); PG8_BAR; PG8_MMA(0, 0, At, B0); PG8_MMA(0, 1, At, B1); PG8_BAR; PG8_SCHED;
	s_setprio 1
	s_waitcnt lgkmcnt(0)
	v_mfma_f32_16x16x32_bf16 v[62:65], v[140:143], v[178:181], v[62:65]
	v_mfma_f32_16x16x32_bf16 v[58:61], v[154:157], v[178:181], v[58:61]
	v_mfma_f32_16x16x32_bf16 v[46:49], v[140:143], v[186:189], v[46:49]
	v_mfma_f32_16x16x32_bf16 v[42:45], v[154:157], v[186:189], v[42:45]
	v_mfma_f32_16x16x32_bf16 v[30:33], v[140:143], v[206:209], v[30:33]
	v_mfma_f32_16x16x32_bf16 v[26:29], v[154:157], v[206:209], v[26:29]
	v_mfma_f32_16x16x32_bf16 v[14:17], v[140:143], v[214:217], v[14:17]
	v_mfma_f32_16x16x32_bf16 v[10:13], v[154:157], v[214:217], v[10:13]
	v_mfma_f32_16x16x32_bf16 v[62:65], v[144:147], v[182:185], v[62:65]
	v_mfma_f32_16x16x32_bf16 v[58:61], v[158:161], v[182:185], v[58:61]
	v_mfma_f32_16x16x32_bf16 v[46:49], v[144:147], v[190:193], v[46:49]
	v_mfma_f32_16x16x32_bf16 v[42:45], v[158:161], v[190:193], v[42:45]
	v_mfma_f32_16x16x32_bf16 v[30:33], v[144:147], v[210:213], v[30:33]
	v_mfma_f32_16x16x32_bf16 v[26:29], v[158:161], v[210:213], v[26:29]
	v_mfma_f32_16x16x32_bf16 v[14:17], v[144:147], v[218:221], v[14:17]
	v_mfma_f32_16x16x32_bf16 v[10:13], v[158:161], v[218:221], v[10:13]
	s_setprio 0
	s_setprio 1
	v_mfma_f32_16x16x32_bf16 v[54:57], v[162:165], v[178:181], v[54:57]
	v_mfma_f32_16x16x32_bf16 v[50:53], v[170:173], v[178:181], v[50:53]
	v_mfma_f32_16x16x32_bf16 v[38:41], v[162:165], v[186:189], v[38:41]
	v_mfma_f32_16x16x32_bf16 v[34:37], v[170:173], v[186:189], v[34:37]
	v_mfma_f32_16x16x32_bf16 v[22:25], v[162:165], v[206:209], v[22:25]
	v_mfma_f32_16x16x32_bf16 v[18:21], v[170:173], v[206:209], v[18:21]
	v_mfma_f32_16x16x32_bf16 v[6:9], v[162:165], v[214:217], v[6:9]
	v_mfma_f32_16x16x32_bf16 v[2:5], v[170:173], v[214:217], v[2:5]
	v_mfma_f32_16x16x32_bf16 v[54:57], v[166:169], v[182:185], v[54:57]
	v_mfma_f32_16x16x32_bf16 v[50:53], v[174:177], v[182:185], v[50:53]
	v_mfma_f32_16x16x32_bf16 v[38:41], v[166:169], v[190:193], v[38:41]
	v_mfma_f32_16x16x32_bf16 v[34:37], v[174:177], v[190:193], v[34:37]
	v_mfma_f32_16x16x32_bf16 v[22:25], v[166:169], v[210:213], v[22:25]
	v_mfma_f32_16x16x32_bf16 v[18:21], v[174:177], v[210:213], v[18:21]
	v_mfma_f32_16x16x32_bf16 v[6:9], v[166:169], v[218:221], v[6:9]
	v_mfma_f32_16x16x32_bf16 v[2:5], v[174:177], v[218:221], v[2:5]
	s_setprio 0
	s_barrier
	s_add_i32 s56, 0, 0x18000
	s_add_i32 s57, 0, 0x1c000
	v_add_u32_e32 v158, s56, v151
	v_add_u32_e32 v174, s57, v151
	ds_read_b128 v[140:143], v158
	ds_read_b128 v[144:147], v158 offset:1024
	ds_read_b128 v[154:157], v158 offset:2048
	ds_read_b128 v[158:161], v158 offset:3072
	ds_read_b128 v[162:165], v174
	ds_read_b128 v[166:169], v174 offset:1024
	ds_read_b128 v[170:173], v174 offset:2048
	ds_read_b128 v[174:177], v174 offset:3072
	s_add_u32 s22, s46, 0x190000
	s_addc_u32 s23, s47, 0
	s_mov_b32 m0, s48
	v_lshl_add_u64 v[242:243], s[22:23], 0, v[130:131]
	ds_read_b128 v[178:181], v153 offset:32768
	ds_read_b128 v[182:185], v153 offset:33792
	ds_read_b128 v[186:189], v153 offset:34816
	ds_read_b128 v[190:193], v153 offset:35840
	ds_read_b128 v[206:209], v153 offset:36864
	ds_read_b128 v[210:213], v153 offset:37888
	ds_read_b128 v[214:217], v153 offset:38912
	ds_read_b128 v[218:221], v153 offset:39936
	global_load_lds_dwordx4 v[242:243], off
	v_lshl_add_u64 v[242:243], s[22:23], 0, v[132:133]
	s_mov_b32 m0, s49
	s_nop 0
	global_load_lds_dwordx4 v[242:243], off
	s_waitcnt vmcnt(8)
	s_waitcnt lgkmcnt(0)
	s_barrier
	s_setprio 1
	s_waitcnt lgkmcnt(0)
	v_mfma_f32_16x16x32_bf16 v[126:129], v[140:143], v[178:181], v[126:129]
	v_mfma_f32_16x16x32_bf16 v[122:125], v[154:157], v[178:181], v[122:125]
	v_mfma_f32_16x16x32_bf16 v[110:113], v[140:143], v[186:189], v[110:113]
	v_mfma_f32_16x16x32_bf16 v[106:109], v[154:157], v[186:189], v[106:109]
	v_mfma_f32_16x16x32_bf16 v[94:97], v[140:143], v[206:209], v[94:97]
	v_mfma_f32_16x16x32_bf16 v[90:93], v[154:157], v[206:209], v[90:93]
	v_mfma_f32_16x16x32_bf16 v[78:81], v[140:143], v[214:217], v[78:81]
	v_mfma_f32_16x16x32_bf16 v[74:77], v[154:157], v[214:217], v[74:77]
	v_mfma_f32_16x16x32_bf16 v[126:129], v[144:147], v[182:185], v[126:129]
	v_mfma_f32_16x16x32_bf16 v[122:125], v[158:161], v[182:185], v[122:125]
	v_mfma_f32_16x16x32_bf16 v[110:113], v[144:147], v[190:193], v[110:113]
	v_mfma_f32_16x16x32_bf16 v[106:109], v[158:161], v[190:193], v[106:109]
	v_mfma_f32_16x16x32_bf16 v[94:97], v[144:147], v[210:213], v[94:97]
	v_mfma_f32_16x16x32_bf16 v[90:93], v[158:161], v[210:213], v[90:93]
	v_mfma_f32_16x16x32_bf16 v[78:81], v[144:147], v[218:221], v[78:81]
	v_mfma_f32_16x16x32_bf16 v[74:77], v[158:161], v[218:221], v[74:77]
	s_setprio 0
	s_setprio 1
	v_mfma_f32_16x16x32_bf16 v[118:121], v[162:165], v[178:181], v[118:121]
	v_mfma_f32_16x16x32_bf16 v[114:117], v[170:173], v[178:181], v[114:117]
	v_mfma_f32_16x16x32_bf16 v[102:105], v[162:165], v[186:189], v[102:105]
	v_mfma_f32_16x16x32_bf16 v[98:101], v[170:173], v[186:189], v[98:101]
	v_mfma_f32_16x16x32_bf16 v[86:89], v[162:165], v[206:209], v[86:89]
	v_mfma_f32_16x16x32_bf16 v[82:85], v[170:173], v[206:209], v[82:85]
	v_mfma_f32_16x16x32_bf16 v[70:73], v[162:165], v[214:217], v[70:73]
	v_mfma_f32_16x16x32_bf16 v[66:69], v[170:173], v[214:217], v[66:69]
	v_mfma_f32_16x16x32_bf16 v[118:121], v[166:169], v[182:185], v[118:121]
	v_mfma_f32_16x16x32_bf16 v[114:117], v[174:177], v[182:185], v[114:117]
	v_mfma_f32_16x16x32_bf16 v[102:105], v[166:169], v[190:193], v[102:105]
	v_mfma_f32_16x16x32_bf16 v[98:101], v[174:177], v[190:193], v[98:101]
	v_mfma_f32_16x16x32_bf16 v[86:89], v[166:169], v[210:213], v[86:89]
	v_mfma_f32_16x16x32_bf16 v[82:85], v[174:177], v[210:213], v[82:85]
	v_mfma_f32_16x16x32_bf16 v[70:73], v[166:169], v[218:221], v[70:73]
	v_mfma_f32_16x16x32_bf16 v[66:69], v[174:177], v[218:221], v[66:69]
	s_setprio 0
	s_barrier
; #define PG8_STAGE(bufoff, gbase, voff) do { _Pragma("unroll") for (int _i = 0; _i < 2; ++_i) \
;         __builtin_amdgcn_global_load_lds((const unsigned*)((const char*)(gbase) + (voff)[_i]), (LAS unsigned*)(lds + (bufoff) + ldsw + _i * 8192), 16, 0, 0); } while (0)
; #define PG8_LDA(dst, b, h) do { _Pragma("unroll") for (int m = 0; m < 4; ++m) _Pragma("unroll") for (int k = 0; k < 2; ++k) dst[m][k] = *(const LAS bf16x8*)(lds + PG8_SA(b, h) + aoff + m * 2048 + k * 1024); } while (0)
; #define PG8_MMA(ai, bj, At, Bt) do { __builtin_amdgcn_s_setprio(1); _Pragma("unroll") for (int m = 0; m < 4; ++m) _Pragma("unroll") for (int n = 0; n < 2; ++n) _Pragma("unroll") for (int k = 0; k < 2; ++k) \
;         acc[ai][bj][m][n] = __builtin_amdgcn_mfma_f32_16x16x32_bf16(Bt[n][k], At[m][k], acc[ai][bj][m][n], 0, 0, 0); __builtin_amdgcn_s_setprio(0); } while (0)
; #define PG8_WAIT_V(n) asm volatile("s_waitcnt vmcnt(" #n ")" ::: "memory")
; #define PG8_WAIT_L(n) asm volatile("s_waitcnt lgkmcnt(" #n ")" ::: "memory")
; #define PG8_BAR __builtin_amdgcn_s_barrier()
; #define PG8_SCHED __builtin_amdgcn_sched_barrier(0)
; template <class Epi, class Sched>
; __device__ __forceinline__ void gemm_phase(LAS unsigned char* lds, const int lda, const int ldb, const Sched& S, const Epi& E) {
;     ...
;         for (int t = 0; t < nt; t += 2) {
;     ...
;             PG8_LDA(At, 1, 1); PG8_STAGE(PG8_SB(1, 0), b3, voffB); PG8_STAGE(PG8_SB(1, 1), b3 + hstepB, voffB); PG8_STAGE(PG8_SA(1, 0), a3, voffA);
;             PG8_WAIT_V(8); PG8_WAIT_L(0); PG8_BAR; PG8_MMA(1, 0, At, B0); PG8_MMA(1, 1, At, B1); PG8_BAR; PG8_SCHED;
;         }
	s_add_i32 s22, s56, s28
	v_lshl_add_u64 v[148:149], v[148:149], 0, s[82:83]
	s_mov_b32 m0, s22
	ds_read_b128 v[178:181], v153 offset:49152
	ds_read_b128 v[182:185], v153 offset:50176
	ds_read_b128 v[186:189], v153 offset:51200
	ds_read_b128 v[190:193], v153 offset:52224
	ds_read_b128 v[206:209], v153 offset:53248
	ds_read_b128 v[210:213], v153 offset:54272
	ds_read_b128 v[214:217], v153 offset:55296
	ds_read_b128 v[218:221], v153 offset:56320
	global_load_lds_dwordx4 v[148:149], off
	s_add_i32 m0, s22, 0x2000
	s_add_u32 s22, s44, 0x40080
	v_lshl_add_u64 v[148:149], v[222:223], 0, s[82:83]
	s_addc_u32 s23, s45, 0
	s_add_i32 s44, s57, s28
	global_load_lds_dwordx4 v[148:149], off
	v_lshl_add_u64 v[148:149], s[22:23], 0, v[0:1]
	s_mov_b32 m0, s44
	s_nop 0
	global_load_lds_dwordx4 v[148:149], off
	v_lshl_add_u64 v[148:149], s[22:23], 0, v[134:135]
	s_add_i32 m0, s44, 0x2000
	s_nop 0
	global_load_lds_dwordx4 v[148:149], off
	v_lshl_add_u64 v[148:149], v[224:225], 0, s[82:83]
	s_mov_b32 m0, s51
	s_nop 0
	global_load_lds_dwordx4 v[148:149], off
	v_lshl_add_u64 v[148:149], v[240:241], 0, s[82:83]
	s_mov_b32 m0, s52
	s_nop 0
	global_load_lds_dwordx4 v[148:149], off
	s_waitcnt vmcnt(8)
	s_waitcnt lgkmcnt(0)
	s_barrier
	s_setprio 1
	s_waitcnt lgkmcnt(0)
	v_mfma_f32_16x16x32_bf16 v[62:65], v[140:143], v[178:181], v[62:65]
	v_mfma_f32_16x16x32_bf16 v[58:61], v[154:157], v[178:181], v[58:61]
	v_mfma_f32_16x16x32_bf16 v[46:49], v[140:143], v[186:189], v[46:49]
	v_mfma_f32_16x16x32_bf16 v[42:45], v[154:157], v[186:189], v[42:45]
	v_mfma_f32_16x16x32_bf16 v[30:33], v[140:143], v[206:209], v[30:33]
	v_mfma_f32_16x16x32_bf16 v[26:29], v[154:157], v[206:209], v[26:29]
	v_mfma_f32_16x16x32_bf16 v[14:17], v[140:143], v[214:217], v[14:17]
	v_mfma_f32_16x16x32_bf16 v[10:13], v[154:157], v[214:217], v[10:13]
	v_mfma_f32_16x16x32_bf16 v[62:65], v[144:147], v[182:185], v[62:65]
	v_mfma_f32_16x16x32_bf16 v[58:61], v[158:161], v[182:185], v[58:61]
	v_mfma_f32_16x16x32_bf16 v[46:49], v[144:147], v[190:193], v[46:49]
	v_mfma_f32_16x16x32_bf16 v[42:45], v[158:161], v[190:193], v[42:45]
	v_mfma_f32_16x16x32_bf16 v[30:33], v[144:147], v[210:213], v[30:33]
	v_mfma_f32_16x16x32_bf16 v[26:29], v[158:161], v[210:213], v[26:29]
	v_mfma_f32_16x16x32_bf16 v[14:17], v[144:147], v[218:221], v[14:17]
	v_mfma_f32_16x16x32_bf16 v[10:13], v[158:161], v[218:221], v[10:13]
	s_setprio 0
	s_setprio 1
	v_mfma_f32_16x16x32_bf16 v[54:57], v[162:165], v[178:181], v[54:57]
	v_mfma_f32_16x16x32_bf16 v[50:53], v[170:173], v[178:181], v[50:53]
	v_mfma_f32_16x16x32_bf16 v[38:41], v[162:165], v[186:189], v[38:41]
	v_mfma_f32_16x16x32_bf16 v[34:37], v[170:173], v[186:189], v[34:37]
	v_mfma_f32_16x16x32_bf16 v[22:25], v[162:165], v[206:209], v[22:25]
	v_mfma_f32_16x16x32_bf16 v[18:21], v[170:173], v[206:209], v[18:21]
	v_mfma_f32_16x16x32_bf16 v[6:9], v[162:165], v[214:217], v[6:9]
	v_mfma_f32_16x16x32_bf16 v[2:5], v[170:173], v[214:217], v[2:5]
	v_mfma_f32_16x16x32_bf16 v[54:57], v[166:169], v[182:185], v[54:57]
	v_mfma_f32_16x16x32_bf16 v[50:53], v[174:177], v[182:185], v[50:53]
	v_mfma_f32_16x16x32_bf16 v[38:41], v[166:169], v[190:193], v[38:41]
	v_mfma_f32_16x16x32_bf16 v[34:37], v[174:177], v[190:193], v[34:37]
	v_mfma_f32_16x16x32_bf16 v[22:25], v[166:169], v[210:213], v[22:25]
	v_mfma_f32_16x16x32_bf16 v[18:21], v[174:177], v[210:213], v[18:21]
	v_mfma_f32_16x16x32_bf16 v[6:9], v[166:169], v[218:221], v[6:9]
	v_mfma_f32_16x16x32_bf16 v[2:5], v[174:177], v[218:221], v[2:5]
	s_add_i32 s25, s25, 2
	s_add_u32 s17, s17, 0x100
	s_addc_u32 s24, s24, 0
	s_cmp_gt_u32 s25, 13
	s_mov_b64 s[22:23], s[36:37]
	s_setprio 0
	s_barrier
	s_cbranch_scc0 .LBB0_802
	s_and_b64 vcc, exec, s[14:15]
	s_cbranch_vccz .LBB0_805
	s_barrier
